# baseline (speedup 1.0000x reference)
; DI unsigned cvtpk(float lo, float hi) { f32x2_t v = {lo, hi}; bf16x2_t b = __builtin_convertvector(v, bf16x2_t); return __builtin_bit_cast(unsigned, b); }
; DI int crow(int g, int h) { return (g & 3) + 8 * (g >> 2) + 4 * h; }
; template <bool GLA, int MODE> ...
;     ...
;             for (int kt = 0; kt < KT; ++kt)
; #pragma unroll
;                 for (int s = 0; s < 2; ++s) {
;                     u32x4 pw; pw.x = cvtpk(S[kt][8 * s + 0], S[kt][8 * s + 1]); pw.y = cvtpk(S[kt][8 * s + 2], S[kt][8 * s + 3]); pw.z = cvtpk(S[kt][8 * s + 4], S[kt][8 * s + 5]); pw.w = cvtpk(S[kt][8 * s + 6], S[kt][8 * s + 7]);
;                     const bf16x8 sb = __builtin_bit_cast(bf16x8, pw);
; #pragma unroll
;                     for (int it = 0; it < 2; ++it) {
;                         const unsigned char* qp = lds + S_QE + (32 * it + r) * S_QES + (hu * DK + 32 * kt + 16 * s + 4 * hh) * 2;
;                         const u32x2 lo = *(const u32x2*)qp, hi = *(const u32x2*)(qp + 16);
;                         u32x4 av; av.x = lo.x; av.y = lo.y; av.z = hi.x; av.w = hi.y;
;                         oa[it] = MFMA32(__builtin_bit_cast(bf16x8, av), sb, oa[it]);
;                     }
;                 }
; #pragma unroll
;         for (int i = 0; i < 4; ++i) *(u32x4*)(lds + S_VT + (tid >> 1) * S_TS + (16 * i + 8 * (tid & 1)) * 2) = vv[i];
;             __syncthreads();
;         }
; #pragma unroll
;         for (int js = 0; js < 4; ++js) {
;             const bf16x8 vb = *(const bf16x8*)(lds + S_VT + (hu * DVH + dv0 + r) * S_TS + (16 * js + 8 * hh) * 2);
;             if (MODE == 0) {
;                 if (js < 2) { const bf16x8 a0 = *(const bf16x8*)(lds + S_ATT + hu * 64 * S_TS + r * S_TS + (16 * js + 8 * hh) * 2); oa[0] = MFMA32(a0, vb, oa[0]); }
;                 { const bf16x8 a1 = *(const bf16x8*)(lds + S_ATT + hu * 64 * S_TS + (32 + r) * S_TS + (16 * js + 8 * hh) * 2); oa[1] = MFMA32(a1, vb, oa[1]); }
;             }
; #pragma unroll
;             for (int kt = 0; kt < KT; ++kt) {
;                 const bf16x8 ka = *(const bf16x8*)(lds + S_KST + (hu * DK + 32 * kt + r) * S_TS + (16 * js + 8 * hh) * 2);
;                 S[kt] = MFMA32(ka, vb, S[kt]);
;             }
;         }
; #pragma unroll
;         for (int kt = 0; kt < KT; ++kt)
; #pragma unroll
;             for (int g = 0; g < 16; ++g) S[kt][g] *= DEC[hu * DK + 32 * kt + crow(g, hh)];
.LBB0_1379:
	s_or_b64 exec, exec, s[86:87]
	ds_read2_b64 v[34:37], v134 offset1:2
	ds_read2_b64 v[142:145], v134 offset0:4 offset1:6
	v_cvt_pk_bf16_f32 v50, v18, v19
	v_cvt_pk_bf16_f32 v51, v20, v21
	v_cvt_pk_bf16_f32 v52, v22, v23
	v_cvt_pk_bf16_f32 v53, v24, v25
	v_add_u32_e32 v150, 0x2000, v134
	ds_read2_b64 v[54:57], v150 offset0:64 offset1:66
	s_waitcnt lgkmcnt(2)
	v_mfma_f32_32x32x16_bf16 v[34:49], v[34:37], v[50:53], 0
	v_cvt_pk_bf16_f32 v146, v26, v27
	v_cvt_pk_bf16_f32 v147, v28, v29
	v_cvt_pk_bf16_f32 v148, v30, v31
	v_cvt_pk_bf16_f32 v149, v32, v33
	s_add_i32 s5, s5, 64
	s_cmp_eq_u32 s38, s9
	s_waitcnt lgkmcnt(1)
	v_mfma_f32_32x32x16_bf16 v[34:49], v[142:145], v[146:149], v[34:49]
	ds_read2_b64 v[142:145], v150 offset0:68 offset1:70
	s_waitcnt lgkmcnt(1)
	v_mfma_f32_32x32x16_bf16 v[50:65], v[54:57], v[50:53], 0
	s_waitcnt lgkmcnt(0)
	v_mfma_f32_32x32x16_bf16 v[50:65], v[142:145], v[146:149], v[50:65]
	ds_read2_b64 v[146:149], v134 offset0:8 offset1:10
	v_cvt_pk_bf16_f32 v142, v2, v3
	v_cvt_pk_bf16_f32 v143, v4, v5
	v_cvt_pk_bf16_f32 v144, v6, v7
	v_cvt_pk_bf16_f32 v145, v8, v9
	s_waitcnt lgkmcnt(0)
	s_nop 0
	v_mfma_f32_32x32x16_bf16 v[34:49], v[146:149], v[142:145], v[34:49]
	ds_read2_b64 v[146:149], v150 offset0:72 offset1:74
	s_waitcnt lgkmcnt(0)
	v_mfma_f32_32x32x16_bf16 v[50:65], v[146:149], v[142:145], v[50:65]
	ds_read2_b64 v[146:149], v134 offset0:12 offset1:14
	v_cvt_pk_bf16_f32 v142, v10, v11
	v_cvt_pk_bf16_f32 v143, v12, v13
	v_cvt_pk_bf16_f32 v144, v14, v15
	v_cvt_pk_bf16_f32 v145, v16, v17
	s_waitcnt lgkmcnt(0)
	s_nop 0
	v_mfma_f32_32x32x16_bf16 v[34:49], v[146:149], v[142:145], v[34:49]
	ds_read2_b64 v[146:149], v150 offset0:76 offset1:78
	s_cbranch_scc1 .Lmy_ladr_last
	s_waitcnt vmcnt(7)
	ds_write_b128 v135, v[82:85] offset:53248
	s_waitcnt vmcnt(6)
	ds_write_b128 v135, v[86:89] offset:53280
	s_waitcnt vmcnt(5)
	ds_write_b128 v135, v[90:93] offset:53312
	s_waitcnt vmcnt(4)
	ds_write_b128 v135, v[94:97] offset:53344
	s_branch .Lmy_ladr_join
.Lmy_ladr_last:
	s_waitcnt vmcnt(3)
	ds_write_b128 v135, v[82:85] offset:53248
	s_waitcnt vmcnt(2)
	ds_write_b128 v135, v[86:89] offset:53280
	s_waitcnt vmcnt(1)
	ds_write_b128 v135, v[90:93] offset:53312
	s_waitcnt vmcnt(0)
	ds_write_b128 v135, v[94:97] offset:53344
.Lmy_ladr_join:
	s_waitcnt lgkmcnt(0)
	s_barrier
	ds_read_b128 v[82:85], v136 offset:53248
	ds_read_b128 v[86:89], v136 offset:53280
	ds_read_b128 v[90:93], v137
	ds_read_b128 v[94:97], v137 offset:32
	v_mfma_f32_32x32x16_bf16 v[50:65], v[146:149], v[142:145], v[50:65]
	s_waitcnt lgkmcnt(1)
	v_mfma_f32_32x32x16_bf16 v[34:49], v[90:93], v[82:85], v[34:49]
	ds_read_b128 v[90:93], v137 offset:4608
	ds_read_b128 v[142:145], v138 offset:34816
	ds_read_b128 v[146:149], v138 offset:34848
	s_waitcnt lgkmcnt(1)
	v_mfma_f32_32x32x16_bf16 v[18:33], v[142:145], v[82:85], v[18:33]
	ds_read_b128 v[142:145], v138 offset:39424
	s_waitcnt lgkmcnt(0)
	v_mfma_f32_32x32x16_bf16 v[2:17], v[142:145], v[82:85], v[2:17]
	v_mfma_f32_32x32x16_bf16 v[50:65], v[90:93], v[82:85], v[50:65]
	ds_read_b128 v[82:85], v137 offset:4640
	ds_read_b128 v[90:93], v138 offset:39456
	v_mfma_f32_32x32x16_bf16 v[18:33], v[146:149], v[86:89], v[18:33]
	v_mfma_f32_32x32x16_bf16 v[34:49], v[94:97], v[86:89], v[34:49]
	s_waitcnt lgkmcnt(0)
	v_mfma_f32_32x32x16_bf16 v[2:17], v[90:93], v[86:89], v[2:17]
	s_nop 9
	v_cvt_pk_bf16_f32 v34, v34, s0
	v_mfma_f32_32x32x16_bf16 v[50:65], v[82:85], v[86:89], v[50:65]
	ds_read_b128 v[82:85], v136 offset:53312
	ds_read_b128 v[86:89], v137 offset:4672
	ds_read_b128 v[90:93], v138 offset:34880
	s_waitcnt lgkmcnt(0)
	v_mfma_f32_32x32x16_bf16 v[18:33], v[90:93], v[82:85], v[18:33]
	ds_read_b128 v[90:93], v138 offset:39488
	s_waitcnt lgkmcnt(0)
	v_mfma_f32_32x32x16_bf16 v[2:17], v[90:93], v[82:85], v[2:17]
	v_mfma_f32_32x32x16_bf16 v[50:65], v[86:89], v[82:85], v[50:65]
	ds_read_b128 v[82:85], v136 offset:53344
	ds_read_b128 v[86:89], v137 offset:4704
	ds_read_b128 v[90:93], v138 offset:34912
	s_waitcnt lgkmcnt(0)
	v_mfma_f32_32x32x16_bf16 v[18:33], v[90:93], v[82:85], v[18:33]
	ds_read_b128 v[90:93], v138 offset:39520
	s_waitcnt lgkmcnt(0)
	v_mfma_f32_32x32x16_bf16 v[2:17], v[90:93], v[82:85], v[2:17]
	v_mfma_f32_32x32x16_bf16 v[50:65], v[86:89], v[82:85], v[50:65]
	ds_read_b128 v[82:85], v139
	ds_read_b128 v[86:89], v139 offset:32
	s_waitcnt lgkmcnt(1)
	s_nop 4
	v_mul_f32_e64 v18, v18, v82
	v_mul_f32_e64 v19, v19, v83
	v_pk_mul_f32 v[20:21], v[20:21], v[84:85]
	ds_read_b128 v[82:85], v139 offset:64
	s_waitcnt lgkmcnt(1)
	v_pk_mul_f32 v[24:25], v[24:25], v[88:89]
	v_pk_mul_f32 v[22:23], v[22:23], v[86:87]
	s_waitcnt lgkmcnt(0)
	v_pk_mul_f32 v[26:27], v[26:27], v[82:83]
	v_pk_mul_f32 v[28:29], v[28:29], v[84:85]
	ds_read_b128 v[82:85], v139 offset:96
	s_waitcnt lgkmcnt(0)
	v_pk_mul_f32 v[30:31], v[30:31], v[82:83]
	v_pk_mul_f32 v[32:33], v[32:33], v[84:85]
	ds_read_b128 v[82:85], v139 offset:128
	s_waitcnt lgkmcnt(0)
	v_pk_mul_f32 v[2:3], v[2:3], v[82:83]
	v_pk_mul_f32 v[4:5], v[4:5], v[84:85]
	ds_read_b128 v[82:85], v139 offset:160
	s_waitcnt lgkmcnt(0)
	v_pk_mul_f32 v[6:7], v[6:7], v[82:83]
	v_pk_mul_f32 v[8:9], v[8:9], v[84:85]
	ds_read_b128 v[82:85], v139 offset:192
	s_waitcnt lgkmcnt(0)
	v_pk_mul_f32 v[10:11], v[10:11], v[82:83]
	v_pk_mul_f32 v[12:13], v[12:13], v[84:85]
	ds_read_b128 v[82:85], v139 offset:224
	s_waitcnt lgkmcnt(0)
	s_barrier
; DI unsigned short f2bf(float f) { return (unsigned short)(cvtpk(f, 0.f) & 0xffffu); }
; DI float bflo(unsigned w) { return __uint_as_float(w << 16); }
; DI float bfhi(unsigned w) { return __uint_as_float(w & 0xffff0000u); }
; DI int crow(int g, int h) { return (g & 3) + 8 * (g >> 2) + 4 * h; }
; template <bool GLA, int MODE> ...
;     ...
;                 unsigned short* OB = (unsigned short*)(lds + S_OB);
; #pragma unroll
;                 for (int it = 0; it < 2; ++it)
; #pragma unroll
;                     for (int g = 0; g < 16; ++g) OB[(32 * it + crow(g, hh)) * (S_OBS / 2) + hu * DVH + dv0 + r] = f2bf(oa[it][g]);
;             }
;             __syncthreads();
;             {
;                 const int i = tid >> 3, p = tid & 7;
;                 const u32x4* src = (const u32x4*)(lds + S_OB + i * S_OBS + p * 64);
;                 float x[32];
; #pragma unroll
;                 for (int q = 0; q < 4; ++q) { const u32x4 w = src[q];
;                     x[8 * q + 0] = bflo(w.x); x[8 * q + 1] = bfhi(w.x); x[8 * q + 2] = bflo(w.y); x[8 * q + 3] = bfhi(w.y);
;                     x[8 * q + 4] = bflo(w.z); x[8 * q + 5] = bfhi(w.z); x[8 * q + 6] = bflo(w.w); x[8 * q + 7] = bfhi(w.w); }
;                 float s = 0.f;
;                 if (!GLA) {
; #pragma unroll
;                     for (int q = 0; q < 32; ++q) s += x[q];
;                     s += __shfl_xor(s, 1); s += __shfl_xor(s, 2);
;                     const float mean = s * (1.f / 128.f);
; #pragma unroll
;                     for (int q = 0; q < 32; ++q) x[q] -= mean;
;                 }
;                 float s2 = 0.f;
; #pragma unroll
;                 for (int q = 0; q < 32; ++q) s2 += x[q] * x[q];
;                 s2 += __shfl_xor(s2, 1); s2 += __shfl_xor(s2, 2); if (GLA) s2 += __shfl_xor(s2, 4);
;                 const float rstd = 1.f / sqrtf(s2 * (1.f / DVH) + EPS);
;                 const float* gp = gain + 32 * p;
	ds_write_b16 v140, v34
	v_cvt_pk_bf16_f32 v34, v35, s0
	ds_write_b16 v140, v34 offset:528
	v_cvt_pk_bf16_f32 v34, v36, s0
	ds_write_b16 v140, v34 offset:1056
	v_cvt_pk_bf16_f32 v34, v37, s0
	ds_write_b16 v140, v34 offset:1584
	v_cvt_pk_bf16_f32 v34, v38, s0
	ds_write_b16 v140, v34 offset:4224
	v_cvt_pk_bf16_f32 v34, v39, s0
	ds_write_b16 v140, v34 offset:4752
	v_cvt_pk_bf16_f32 v34, v40, s0
	ds_write_b16 v140, v34 offset:5280
	v_cvt_pk_bf16_f32 v34, v41, s0
	ds_write_b16 v140, v34 offset:5808
	v_cvt_pk_bf16_f32 v34, v42, s0
	ds_write_b16 v140, v34 offset:8448
	v_cvt_pk_bf16_f32 v34, v43, s0
	ds_write_b16 v140, v34 offset:8976
	v_cvt_pk_bf16_f32 v34, v44, s0
	ds_write_b16 v140, v34 offset:9504
	v_cvt_pk_bf16_f32 v34, v45, s0
	ds_write_b16 v140, v34 offset:10032
	v_cvt_pk_bf16_f32 v34, v46, s0
	ds_write_b16 v140, v34 offset:12672
	v_cvt_pk_bf16_f32 v34, v47, s0
	ds_write_b16 v140, v34 offset:13200
	v_cvt_pk_bf16_f32 v34, v48, s0
	ds_write_b16 v140, v34 offset:13728
	v_cvt_pk_bf16_f32 v34, v49, s0
	ds_write_b16 v140, v34 offset:14256
	v_cvt_pk_bf16_f32 v34, v50, s0
	ds_write_b16 v140, v34 offset:16896
	v_cvt_pk_bf16_f32 v34, v51, s0
	ds_write_b16 v140, v34 offset:17424
	v_cvt_pk_bf16_f32 v34, v52, s0
	ds_write_b16 v140, v34 offset:17952
	v_cvt_pk_bf16_f32 v34, v53, s0
	ds_write_b16 v140, v34 offset:18480
	v_cvt_pk_bf16_f32 v34, v54, s0
	ds_write_b16 v140, v34 offset:21120
	v_cvt_pk_bf16_f32 v34, v55, s0
	ds_write_b16 v140, v34 offset:21648
	v_cvt_pk_bf16_f32 v34, v56, s0
	ds_write_b16 v140, v34 offset:22176
	v_cvt_pk_bf16_f32 v34, v57, s0
	ds_write_b16 v140, v34 offset:22704
	v_cvt_pk_bf16_f32 v34, v58, s0
	ds_write_b16 v140, v34 offset:25344
	v_cvt_pk_bf16_f32 v34, v59, s0
	ds_write_b16 v140, v34 offset:25872
	v_cvt_pk_bf16_f32 v34, v60, s0
	ds_write_b16 v140, v34 offset:26400
	v_cvt_pk_bf16_f32 v34, v61, s0
	ds_write_b16 v140, v34 offset:26928
	v_cvt_pk_bf16_f32 v34, v62, s0
	ds_write_b16 v140, v34 offset:29568
	v_cvt_pk_bf16_f32 v34, v63, s0
	ds_write_b16 v140, v34 offset:30096
	v_cvt_pk_bf16_f32 v34, v64, s0
	ds_write_b16 v140, v34 offset:30624
	v_cvt_pk_bf16_f32 v34, v65, s0
	ds_write_b16 v140, v34 offset:31152
	s_waitcnt lgkmcnt(0)
	s_barrier
	ds_read_b128 v[44:47], v141
	ds_read_b128 v[48:51], v141 offset:16
	ds_read_b128 v[52:55], v141 offset:32
	ds_read_b128 v[56:59], v141 offset:48
	v_pk_mul_f32 v[16:17], v[16:17], v[84:85]
	s_waitcnt lgkmcnt(3)
	v_lshlrev_b32_e32 v64, 16, v44
	v_and_b32_e32 v65, 0xffff0000, v44
	v_add_f32_e32 v44, 0, v64
	v_lshlrev_b32_e32 v62, 16, v46
	v_and_b32_e32 v63, 0xffff0000, v46
	v_lshlrev_b32_e32 v46, 16, v45
	v_add_f32_e32 v44, v44, v65
	v_lshlrev_b32_e32 v60, 16, v47
	v_and_b32_e32 v61, 0xffff0000, v47
	v_and_b32_e32 v47, 0xffff0000, v45
	v_add_f32_e32 v44, v44, v46
	v_add_f32_e32 v44, v44, v47
	v_add_f32_e32 v44, v44, v62
	v_add_f32_e32 v44, v44, v63
	v_add_f32_e32 v44, v44, v60
	v_add_f32_e32 v90, v44, v61
	s_waitcnt lgkmcnt(2)
	v_lshlrev_b32_e32 v88, 16, v48
	v_and_b32_e32 v89, 0xffff0000, v48
	v_add_f32_e32 v48, v90, v88
	v_lshlrev_b32_e32 v86, 16, v50
	v_and_b32_e32 v87, 0xffff0000, v50
	v_lshlrev_b32_e32 v50, 16, v49
	v_add_f32_e32 v48, v48, v89
	v_lshlrev_b32_e32 v84, 16, v51
	v_and_b32_e32 v85, 0xffff0000, v51
	v_and_b32_e32 v51, 0xffff0000, v49
	v_add_f32_e32 v48, v48, v50
	v_add_f32_e32 v48, v48, v51
	v_add_f32_e32 v48, v48, v86
	v_add_f32_e32 v48, v48, v87
	v_add_f32_e32 v48, v48, v84
	v_pk_mul_f32 v[14:15], v[14:15], v[82:83]
	s_waitcnt lgkmcnt(0)
	v_and_b32_e32 v44, 0xffff0000, v59
	v_lshlrev_b32_e32 v45, 16, v59
	v_and_b32_e32 v82, 0xffff0000, v58
	v_lshlrev_b32_e32 v83, 16, v58
	v_and_b32_e32 v58, 0xffff0000, v57
	v_lshlrev_b32_e32 v59, 16, v57
	v_add_f32_e32 v57, v48, v85
	v_lshlrev_b32_e32 v92, 16, v52
	v_and_b32_e32 v93, 0xffff0000, v52
	v_add_f32_e32 v52, v57, v92
	v_lshlrev_b32_e32 v90, 16, v54
	v_and_b32_e32 v91, 0xffff0000, v54
	v_lshlrev_b32_e32 v54, 16, v53
	v_add_f32_e32 v52, v52, v93
	v_lshlrev_b32_e32 v48, 16, v55
	v_and_b32_e32 v49, 0xffff0000, v55
	v_and_b32_e32 v55, 0xffff0000, v53
	v_add_f32_e32 v52, v52, v54
	v_add_f32_e32 v52, v52, v55
	v_add_f32_e32 v52, v52, v90
	v_add_f32_e32 v52, v52, v91
	v_add_f32_e32 v52, v52, v48
	v_add_f32_e32 v57, v52, v49
	v_lshlrev_b32_e32 v52, 16, v56
	v_and_b32_e32 v53, 0xffff0000, v56
	v_add_f32_e32 v56, v57, v52
	v_add_f32_e32 v56, v56, v53
	v_add_f32_e32 v56, v56, v59
	v_and_b32_e32 v35, 64, v220
	v_add_f32_e32 v56, v56, v58
	v_xor_b32_e32 v34, 1, v220
	v_add_u32_e32 v35, 64, v35
	v_add_f32_e32 v56, v56, v83
	v_cmp_lt_i32_e32 vcc, v34, v35
	v_add_f32_e32 v56, v56, v82
	v_add_f32_e32 v56, v56, v45
	v_cndmask_b32_e32 v34, v220, v34, vcc
	v_lshlrev_b32_e32 v168, 2, v34
	v_add_f32_e32 v56, v56, v44
	ds_bpermute_b32 v57, v168, v56
	v_xor_b32_e32 v34, 2, v220
	v_cmp_lt_i32_e32 vcc, v34, v35
	s_waitcnt lgkmcnt(0)
	v_add_f32_e32 v56, v56, v57
	v_cndmask_b32_e32 v34, v220, v34, vcc
	v_lshlrev_b32_e32 v169, 2, v34
	v_add_u32_e32 v34, s6, v112
	v_ashrrev_i32_e32 v35, 31, v34
	ds_bpermute_b32 v57, v169, v56
	v_lshlrev_b64 v[34:35], 10, v[34:35]
	v_lshl_add_u64 v[42:43], v[106:107], 0, v[34:35]
	global_load_dwordx4 v[34:37], v[104:105], off offset:16
	global_load_dwordx4 v[38:41], v[104:105], off
	global_load_dwordx4 v[198:201], v[104:105], off offset:48
	global_load_dwordx4 v[202:205], v[104:105], off offset:32
	global_load_dwordx4 v[206:209], v[104:105], off offset:80
	global_load_dwordx4 v[226:229], v[104:105], off offset:64
	global_load_dwordx4 v[230:233], v[104:105], off offset:112
	global_load_dwordx4 v[234:237], v[104:105], off offset:96
	s_mov_b32 s6, 0xf800000
	s_waitcnt lgkmcnt(0)
; DI unsigned cvtpk(float lo, float hi) { f32x2_t v = {lo, hi}; bf16x2_t b = __builtin_convertvector(v, bf16x2_t); return __builtin_bit_cast(unsigned, b); }
; template <bool GLA, int MODE> ...
;     ...
;                     const float mean = s * (1.f / 128.f);
; #pragma unroll
;                     for (int q = 0; q < 32; ++q) x[q] -= mean;
;                 }
;                 float s2 = 0.f;
; #pragma unroll
;                 for (int q = 0; q < 32; ++q) s2 += x[q] * x[q];
;                 s2 += __shfl_xor(s2, 1); s2 += __shfl_xor(s2, 2); if (GLA) s2 += __shfl_xor(s2, 4);
;                 const float rstd = 1.f / sqrtf(s2 * (1.f / DVH) + EPS);
;                 const float* gp = gain + 32 * p;
;                 u32x4* dst = (u32x4*)(OUT + (size_t)(row0 + i) * out_ld + ocol0 + 32 * p);
; #pragma unroll
;                 for (int q = 0; q < 4; ++q) {
;                     u32x4 w;
;                     w.x = cvtpk(x[8 * q + 0] * rstd * gp[8 * q + 0], x[8 * q + 1] * rstd * gp[8 * q + 1]);
;                     w.y = cvtpk(x[8 * q + 2] * rstd * gp[8 * q + 2], x[8 * q + 3] * rstd * gp[8 * q + 3]);
;                     w.z = cvtpk(x[8 * q + 4] * rstd * gp[8 * q + 4], x[8 * q + 5] * rstd * gp[8 * q + 5]);
;                     w.w = cvtpk(x[8 * q + 6] * rstd * gp[8 * q + 6], x[8 * q + 7] * rstd * gp[8 * q + 7]);
;                     dst[q] = w;
;                 }
	v_add_f32_e32 v56, v56, v57
	v_mul_f32_e32 v56, 0x3c000000, v56
	v_pk_add_f32 v[64:65], v[64:65], v[56:57] op_sel_hi:[1,0] neg_lo:[0,1] neg_hi:[0,1]
	v_pk_add_f32 v[46:47], v[46:47], v[56:57] op_sel_hi:[1,0] neg_lo:[0,1] neg_hi:[0,1]
	v_pk_add_f32 v[62:63], v[62:63], v[56:57] op_sel_hi:[1,0] neg_lo:[0,1] neg_hi:[0,1]
	v_pk_add_f32 v[60:61], v[60:61], v[56:57] op_sel_hi:[1,0] neg_lo:[0,1] neg_hi:[0,1]
	v_pk_add_f32 v[88:89], v[88:89], v[56:57] op_sel_hi:[1,0] neg_lo:[0,1] neg_hi:[0,1]
	v_pk_add_f32 v[50:51], v[50:51], v[56:57] op_sel_hi:[1,0] neg_lo:[0,1] neg_hi:[0,1]
	v_pk_add_f32 v[86:87], v[86:87], v[56:57] op_sel_hi:[1,0] neg_lo:[0,1] neg_hi:[0,1]
	v_pk_add_f32 v[84:85], v[84:85], v[56:57] op_sel_hi:[1,0] neg_lo:[0,1] neg_hi:[0,1]
	v_pk_add_f32 v[92:93], v[92:93], v[56:57] op_sel_hi:[1,0] neg_lo:[0,1] neg_hi:[0,1]
	v_pk_add_f32 v[54:55], v[54:55], v[56:57] op_sel_hi:[1,0] neg_lo:[0,1] neg_hi:[0,1]
	v_pk_add_f32 v[90:91], v[90:91], v[56:57] op_sel_hi:[1,0] neg_lo:[0,1] neg_hi:[0,1]
	v_pk_add_f32 v[48:49], v[48:49], v[56:57] op_sel_hi:[1,0] neg_lo:[0,1] neg_hi:[0,1]
	v_pk_add_f32 v[52:53], v[52:53], v[56:57] op_sel_hi:[1,0] neg_lo:[0,1] neg_hi:[0,1]
	v_pk_add_f32 v[58:59], v[58:59], v[56:57] op_sel_hi:[1,0] neg_lo:[0,1] neg_hi:[0,1]
	v_pk_add_f32 v[82:83], v[82:83], v[56:57] op_sel_hi:[1,0] neg_lo:[0,1] neg_hi:[0,1]
	v_pk_add_f32 v[44:45], v[44:45], v[56:57] op_sel_hi:[1,0] neg_lo:[0,1] neg_hi:[0,1]
	v_pk_mul_f32 v[56:57], v[64:65], v[64:65]
	v_pk_mul_f32 v[94:95], v[46:47], v[46:47]
	v_add_f32_e32 v56, v56, v57
	v_add_f32_e32 v56, v94, v56
	v_pk_mul_f32 v[96:97], v[62:63], v[62:63]
	v_add_f32_e32 v56, v95, v56
	v_add_f32_e32 v56, v96, v56
	v_pk_mul_f32 v[142:143], v[60:61], v[60:61]
	v_add_f32_e32 v56, v97, v56
	v_add_f32_e32 v56, v142, v56
	v_pk_mul_f32 v[144:145], v[88:89], v[88:89]
	v_add_f32_e32 v56, v143, v56
	v_add_f32_e32 v56, v144, v56
	v_pk_mul_f32 v[146:147], v[50:51], v[50:51]
	v_add_f32_e32 v56, v145, v56
	v_add_f32_e32 v56, v146, v56
	v_pk_mul_f32 v[148:149], v[86:87], v[86:87]
	v_add_f32_e32 v56, v147, v56
	v_add_f32_e32 v56, v148, v56
	v_pk_mul_f32 v[150:151], v[84:85], v[84:85]
	v_add_f32_e32 v56, v149, v56
	v_add_f32_e32 v56, v150, v56
	v_pk_mul_f32 v[152:153], v[92:93], v[92:93]
	v_add_f32_e32 v56, v151, v56
	v_add_f32_e32 v56, v152, v56
	v_pk_mul_f32 v[154:155], v[54:55], v[54:55]
	v_add_f32_e32 v56, v153, v56
	v_add_f32_e32 v56, v154, v56
	v_pk_mul_f32 v[156:157], v[90:91], v[90:91]
	v_add_f32_e32 v56, v155, v56
	v_add_f32_e32 v56, v156, v56
	v_pk_mul_f32 v[158:159], v[48:49], v[48:49]
	v_add_f32_e32 v56, v157, v56
	v_add_f32_e32 v56, v158, v56
	v_pk_mul_f32 v[160:161], v[52:53], v[52:53]
	v_add_f32_e32 v56, v159, v56
	v_add_f32_e32 v56, v160, v56
	v_pk_mul_f32 v[162:163], v[58:59], v[58:59]
	v_add_f32_e32 v56, v161, v56
	v_add_f32_e32 v56, v163, v56
	v_pk_mul_f32 v[164:165], v[82:83], v[82:83]
	v_add_f32_e32 v56, v162, v56
	v_add_f32_e32 v56, v165, v56
	v_pk_mul_f32 v[166:167], v[44:45], v[44:45]
	v_add_f32_e32 v56, v164, v56
	v_add_f32_e32 v56, v167, v56
	v_add_f32_e32 v56, v166, v56
	ds_bpermute_b32 v57, v168, v56
	s_waitcnt lgkmcnt(0)
	v_add_f32_e32 v56, v56, v57
	ds_bpermute_b32 v57, v169, v56
	s_waitcnt lgkmcnt(0)
	v_add_f32_e32 v56, v56, v57
	v_fmamk_f32 v56, v56, 0x3c000000, v214
	v_cmp_gt_f32_e32 vcc, s6, v56
	v_mul_f32_e32 v57, 0x4f800000, v56
	s_nop 0
	v_cndmask_b32_e32 v56, v56, v57, vcc
	v_sqrt_f32_e32 v57, v56
	s_nop 0
	v_add_u32_e32 v94, -1, v57
	v_fma_f32 v95, -v94, v57, v56
	v_cmp_ge_f32_e64 s[86:87], 0, v95
	v_add_u32_e32 v95, 1, v57
	s_nop 0
	v_cndmask_b32_e64 v94, v57, v94, s[86:87]
	v_fma_f32 v57, -v95, v57, v56
	v_cmp_lt_f32_e64 s[86:87], 0, v57
	s_nop 1
	v_cndmask_b32_e64 v57, v94, v95, s[86:87]
	v_mul_f32_e32 v94, 0x37800000, v57
	v_cndmask_b32_e32 v57, v57, v94, vcc
	v_cmp_class_f32_e32 vcc, v56, v215
	s_nop 1
	v_cndmask_b32_e32 v56, v57, v56, vcc
	v_div_scale_f32 v57, s[6:7], v56, v56, 1.0
	v_rcp_f32_e32 v94, v57
	s_nop 0
	v_fma_f32 v95, -v57, v94, 1.0
	v_fmac_f32_e32 v94, v95, v94
	v_div_scale_f32 v95, vcc, 1.0, v56, 1.0
	v_mul_f32_e32 v96, v95, v94
	v_fma_f32 v97, -v57, v96, v95
	v_fmac_f32_e32 v96, v97, v94
	v_fma_f32 v57, -v57, v96, v95
	v_div_fmas_f32 v57, v57, v94, v96
	v_div_fixup_f32 v56, v57, v56, 1.0
	v_pk_mul_f32 v[64:65], v[64:65], v[56:57] op_sel_hi:[1,0]
	v_pk_mul_f32 v[46:47], v[46:47], v[56:57] op_sel_hi:[1,0]
	s_waitcnt vmcnt(0)
	v_pk_mul_f32 v[38:39], v[38:39], v[64:65]
	v_pk_mul_f32 v[40:41], v[40:41], v[46:47]
	v_cvt_pk_bf16_f32 v38, v38, v39
	v_cvt_pk_bf16_f32 v39, v40, v41
	v_pk_mul_f32 v[40:41], v[62:63], v[56:57] op_sel_hi:[1,0]
	v_pk_mul_f32 v[46:47], v[88:89], v[56:57] op_sel_hi:[1,0]
	v_pk_mul_f32 v[34:35], v[34:35], v[40:41]
	s_nop 0
	v_cvt_pk_bf16_f32 v40, v34, v35
	v_pk_mul_f32 v[34:35], v[60:61], v[56:57] op_sel_hi:[1,0]
	s_nop 0
	v_pk_mul_f32 v[34:35], v[36:37], v[34:35]
	s_nop 0
	v_cvt_pk_bf16_f32 v41, v34, v35
	global_store_dwordx4 v[42:43], v[38:41], off
	s_nop 1
	v_pk_mul_f32 v[38:39], v[202:203], v[46:47]
	v_pk_mul_f32 v[46:47], v[50:51], v[56:57] op_sel_hi:[1,0]
	v_cvt_pk_bf16_f32 v38, v38, v39
	v_pk_mul_f32 v[40:41], v[204:205], v[46:47]
	v_pk_mul_f32 v[46:47], v[92:93], v[56:57] op_sel_hi:[1,0]
	v_cvt_pk_bf16_f32 v39, v40, v41
	v_pk_mul_f32 v[40:41], v[86:87], v[56:57] op_sel_hi:[1,0]
	s_nop 0
	v_pk_mul_f32 v[34:35], v[198:199], v[40:41]
	s_nop 0
	v_cvt_pk_bf16_f32 v40, v34, v35
	v_pk_mul_f32 v[34:35], v[84:85], v[56:57] op_sel_hi:[1,0]
	s_nop 0
	v_pk_mul_f32 v[34:35], v[200:201], v[34:35]
	s_nop 0
	v_cvt_pk_bf16_f32 v41, v34, v35
	global_store_dwordx4 v[42:43], v[38:41], off offset:16
	s_nop 1
	v_pk_mul_f32 v[38:39], v[226:227], v[46:47]
	v_pk_mul_f32 v[46:47], v[54:55], v[56:57] op_sel_hi:[1,0]
	v_cvt_pk_bf16_f32 v38, v38, v39
	v_pk_mul_f32 v[40:41], v[228:229], v[46:47]
	v_pk_mul_f32 v[46:47], v[52:53], v[56:57] op_sel_hi:[1,0]
	v_cvt_pk_bf16_f32 v39, v40, v41
	v_pk_mul_f32 v[40:41], v[90:91], v[56:57] op_sel_hi:[1,0]
	s_nop 0
	v_pk_mul_f32 v[34:35], v[206:207], v[40:41]
	s_nop 0
	v_cvt_pk_bf16_f32 v40, v34, v35
	v_pk_mul_f32 v[34:35], v[48:49], v[56:57] op_sel_hi:[1,0]
	s_nop 0
	v_pk_mul_f32 v[34:35], v[208:209], v[34:35]
	s_nop 0
	v_cvt_pk_bf16_f32 v41, v34, v35
	global_store_dwordx4 v[42:43], v[38:41], off offset:32
	s_nop 1
	v_pk_mul_f32 v[38:39], v[234:235], v[46:47]
	v_pk_mul_f32 v[46:47], v[58:59], v[56:57] op_sel_hi:[1,0]
	v_cvt_pk_bf16_f32 v38, v38, v39
	v_pk_mul_f32 v[40:41], v[236:237], v[46:47] op_sel:[0,1] op_sel_hi:[1,0]
	s_nop 0
	v_cvt_pk_bf16_f32 v39, v40, v41
	v_pk_mul_f32 v[40:41], v[82:83], v[56:57] op_sel_hi:[1,0]
	s_nop 0
	v_pk_mul_f32 v[34:35], v[230:231], v[40:41] op_sel:[0,1] op_sel_hi:[1,0]
	s_nop 0
	v_cvt_pk_bf16_f32 v40, v34, v35
	v_pk_mul_f32 v[34:35], v[44:45], v[56:57] op_sel_hi:[1,0]
	s_nop 0
	v_pk_mul_f32 v[34:35], v[232:233], v[34:35] op_sel:[0,1] op_sel_hi:[1,0]
	s_nop 0
	v_cvt_pk_bf16_f32 v41, v34, v35
	global_store_dwordx4 v[42:43], v[38:41], off offset:48
	s_barrier
	s_cbranch_scc1 .LBB0_1388

; DI unsigned cvtpk(float lo, float hi) { f32x2_t v = {lo, hi}; bf16x2_t b = __builtin_convertvector(v, bf16x2_t); return __builtin_bit_cast(unsigned, b); }
; #define MFMA32(a, b, c) __builtin_amdgcn_mfma_f32_32x32x16_bf16((a), (b), (c), 0, 0, 0)
; template <bool GLA, int MODE> ...
;     ...
;             for (int kt = 0; kt < KT; ++kt)
; #pragma unroll
;                 for (int s = 0; s < 2; ++s) {
;                     u32x4 pw; pw.x = cvtpk(S[kt][8 * s + 0], S[kt][8 * s + 1]); pw.y = cvtpk(S[kt][8 * s + 2], S[kt][8 * s + 3]); pw.z = cvtpk(S[kt][8 * s + 4], S[kt][8 * s + 5]); pw.w = cvtpk(S[kt][8 * s + 6], S[kt][8 * s + 7]);
;                     const bf16x8 sb = __builtin_bit_cast(bf16x8, pw);
; #pragma unroll
;                     for (int it = 0; it < 2; ++it) {
;                         const unsigned char* qp = lds + S_QE + (32 * it + r) * S_QES + (hu * DK + 32 * kt + 16 * s + 4 * hh) * 2;
;                         const u32x2 lo = *(const u32x2*)qp, hi = *(const u32x2*)(qp + 16);
;                         u32x4 av; av.x = lo.x; av.y = lo.y; av.z = hi.x; av.w = hi.y;
;                         oa[it] = MFMA32(__builtin_bit_cast(bf16x8, av), sb, oa[it]);
;                     }
;                 }
; #pragma unroll
;         for (int i = 0; i < 4; ++i) *(u32x4*)(lds + S_VT + (tid >> 1) * S_TS + (16 * i + 8 * (tid & 1)) * 2) = vv[i];
;             __syncthreads();
;         }
; #pragma unroll
;         for (int js = 0; js < 4; ++js) {
;             const bf16x8 vb = *(const bf16x8*)(lds + S_VT + (hu * DVH + dv0 + r) * S_TS + (16 * js + 8 * hh) * 2);
;             if (MODE == 0) {
;                 if (js < 2) { const bf16x8 a0 = *(const bf16x8*)(lds + S_ATT + hu * 64 * S_TS + r * S_TS + (16 * js + 8 * hh) * 2); oa[0] = MFMA32(a0, vb, oa[0]); }
;                 { const bf16x8 a1 = *(const bf16x8*)(lds + S_ATT + hu * 64 * S_TS + (32 + r) * S_TS + (16 * js + 8 * hh) * 2); oa[1] = MFMA32(a1, vb, oa[1]); }
;             }
; #pragma unroll
;             for (int kt = 0; kt < KT; ++kt) {
;                 const bf16x8 ka = *(const bf16x8*)(lds + S_KST + (hu * DK + 32 * kt + r) * S_TS + (16 * js + 8 * hh) * 2);
;                 S[kt] = MFMA32(ka, vb, S[kt]);
.LBB0_1681:
	s_or_b64 exec, exec, s[86:87]
	ds_read2_b64 v[70:73], v160 offset1:2
	ds_read2_b64 v[168:171], v160 offset0:4 offset1:6
	v_cvt_pk_bf16_f32 v66, v2, v3
	v_cvt_pk_bf16_f32 v67, v4, v5
	v_cvt_pk_bf16_f32 v68, v6, v7
	v_cvt_pk_bf16_f32 v69, v8, v9
	v_add_u32_e32 v176, 0x2000, v160
	v_cvt_pk_bf16_f32 v172, v10, v11
	s_waitcnt lgkmcnt(1)
	v_mfma_f32_32x32x16_bf16 v[82:97], v[70:73], v[66:69], 0
	ds_read2_b64 v[70:73], v176 offset0:64 offset1:66
	v_cvt_pk_bf16_f32 v173, v12, v13
	v_cvt_pk_bf16_f32 v174, v14, v15
	v_cvt_pk_bf16_f32 v175, v16, v17
	s_add_i32 s85, s85, 64
	s_cmp_eq_u32 s38, s6
	s_waitcnt lgkmcnt(1)
	v_mfma_f32_32x32x16_bf16 v[82:97], v[168:171], v[172:175], v[82:97]
	ds_read2_b64 v[168:171], v176 offset0:68 offset1:70
	s_waitcnt lgkmcnt(1)
	v_mfma_f32_32x32x16_bf16 v[66:81], v[70:73], v[66:69], 0
	s_waitcnt lgkmcnt(0)
	v_mfma_f32_32x32x16_bf16 v[66:81], v[168:171], v[172:175], v[66:81]
	ds_read2_b64 v[172:175], v160 offset0:8 offset1:10
	v_cvt_pk_bf16_f32 v168, v18, v19
	v_cvt_pk_bf16_f32 v169, v20, v21
	v_cvt_pk_bf16_f32 v170, v22, v23
	v_cvt_pk_bf16_f32 v171, v24, v25
	s_waitcnt lgkmcnt(0)
	s_nop 0
	v_mfma_f32_32x32x16_bf16 v[82:97], v[172:175], v[168:171], v[82:97]
	ds_read2_b64 v[172:175], v176 offset0:72 offset1:74
	s_waitcnt lgkmcnt(0)
	v_mfma_f32_32x32x16_bf16 v[66:81], v[172:175], v[168:171], v[66:81]
	ds_read2_b64 v[172:175], v160 offset0:12 offset1:14
	v_cvt_pk_bf16_f32 v168, v26, v27
	v_cvt_pk_bf16_f32 v169, v28, v29
	v_cvt_pk_bf16_f32 v170, v30, v31
	v_cvt_pk_bf16_f32 v171, v32, v33
	s_waitcnt lgkmcnt(0)
	s_nop 0
	v_mfma_f32_32x32x16_bf16 v[82:97], v[172:175], v[168:171], v[82:97]
	ds_read2_b64 v[172:175], v176 offset0:76 offset1:78
	s_waitcnt lgkmcnt(0)
	v_mfma_f32_32x32x16_bf16 v[66:81], v[172:175], v[168:171], v[66:81]
	ds_read2_b64 v[172:175], v160 offset0:16 offset1:18
	v_cvt_pk_bf16_f32 v168, v34, v35
	v_cvt_pk_bf16_f32 v169, v36, v37
	v_cvt_pk_bf16_f32 v170, v38, v39
	v_cvt_pk_bf16_f32 v171, v40, v41
	s_waitcnt lgkmcnt(0)
	s_nop 0
	v_mfma_f32_32x32x16_bf16 v[82:97], v[172:175], v[168:171], v[82:97]
	ds_read2_b64 v[172:175], v176 offset0:80 offset1:82
	s_waitcnt lgkmcnt(0)
	v_mfma_f32_32x32x16_bf16 v[66:81], v[172:175], v[168:171], v[66:81]
	ds_read2_b64 v[172:175], v160 offset0:20 offset1:22
	v_cvt_pk_bf16_f32 v168, v42, v43
	v_cvt_pk_bf16_f32 v169, v44, v45
	v_cvt_pk_bf16_f32 v170, v46, v47
	v_cvt_pk_bf16_f32 v171, v48, v49
	s_waitcnt lgkmcnt(0)
	s_nop 0
	v_mfma_f32_32x32x16_bf16 v[82:97], v[172:175], v[168:171], v[82:97]
	ds_read2_b64 v[172:175], v176 offset0:84 offset1:86
	s_waitcnt lgkmcnt(0)
	v_mfma_f32_32x32x16_bf16 v[66:81], v[172:175], v[168:171], v[66:81]
	ds_read2_b64 v[172:175], v160 offset0:24 offset1:26
	v_cvt_pk_bf16_f32 v168, v50, v51
	v_cvt_pk_bf16_f32 v169, v52, v53
	v_cvt_pk_bf16_f32 v170, v54, v55
	v_cvt_pk_bf16_f32 v171, v56, v57
	s_waitcnt lgkmcnt(0)
	s_nop 0
	v_mfma_f32_32x32x16_bf16 v[82:97], v[172:175], v[168:171], v[82:97]
	ds_read2_b64 v[172:175], v176 offset0:88 offset1:90
	s_waitcnt lgkmcnt(0)
	v_mfma_f32_32x32x16_bf16 v[66:81], v[172:175], v[168:171], v[66:81]
	ds_read2_b64 v[172:175], v160 offset0:28 offset1:30
	v_cvt_pk_bf16_f32 v168, v58, v59
	v_cvt_pk_bf16_f32 v169, v60, v61
	v_cvt_pk_bf16_f32 v170, v62, v63
	v_cvt_pk_bf16_f32 v171, v64, v65
	s_waitcnt lgkmcnt(0)
	s_nop 0
	v_mfma_f32_32x32x16_bf16 v[82:97], v[172:175], v[168:171], v[82:97]
	ds_read2_b64 v[172:175], v176 offset0:92 offset1:94
	s_cbranch_scc1 .Lmy_ladg_last
	s_waitcnt vmcnt(9)
	ds_write_b128 v161, v[122:125] offset:53248
	s_waitcnt vmcnt(8)
	ds_write_b128 v161, v[126:129] offset:53280
	s_waitcnt vmcnt(7)
	ds_write_b128 v161, v[130:133] offset:53312
	s_waitcnt vmcnt(6)
	ds_write_b128 v161, v[134:137] offset:53344
	s_branch .Lmy_ladg_join
.Lmy_ladg_last:
	s_waitcnt vmcnt(3)
	ds_write_b128 v161, v[122:125] offset:53248
	s_waitcnt vmcnt(2)
	ds_write_b128 v161, v[126:129] offset:53280
	s_waitcnt vmcnt(1)
	ds_write_b128 v161, v[130:133] offset:53312
	s_waitcnt vmcnt(0)
	ds_write_b128 v161, v[134:137] offset:53344
.Lmy_ladg_join:
	s_waitcnt lgkmcnt(0)
	s_barrier
	ds_read_b128 v[122:125], v162 offset:53248
	ds_read_b128 v[126:129], v162 offset:53280
	ds_read_b128 v[130:133], v163
	ds_read_b128 v[134:137], v163 offset:32
	v_mfma_f32_32x32x16_bf16 v[66:81], v[172:175], v[168:171], v[66:81]
	s_waitcnt lgkmcnt(1)
	v_mfma_f32_32x32x16_bf16 v[82:97], v[130:133], v[122:125], v[82:97]
	ds_read_b128 v[130:133], v163 offset:4608
	ds_read_b128 v[168:171], v164 offset:34816
	ds_read_b128 v[172:175], v164 offset:34848
	s_waitcnt lgkmcnt(1)
	v_mfma_f32_32x32x16_bf16 v[2:17], v[168:171], v[122:125], v[2:17]
	ds_read_b128 v[168:171], v164 offset:39424
	s_waitcnt lgkmcnt(0)
	v_mfma_f32_32x32x16_bf16 v[18:33], v[168:171], v[122:125], v[18:33]
	ds_read_b128 v[168:171], v164 offset:44032
	s_waitcnt lgkmcnt(0)
	v_mfma_f32_32x32x16_bf16 v[34:49], v[168:171], v[122:125], v[34:49]
	ds_read_b128 v[168:171], v164 offset:48640
	s_waitcnt lgkmcnt(0)
	v_mfma_f32_32x32x16_bf16 v[50:65], v[168:171], v[122:125], v[50:65]
	v_mfma_f32_32x32x16_bf16 v[66:81], v[130:133], v[122:125], v[66:81]
	ds_read_b128 v[122:125], v163 offset:4640
	ds_read_b128 v[130:133], v164 offset:39456
	s_waitcnt lgkmcnt(0)
	v_mfma_f32_32x32x16_bf16 v[18:33], v[130:133], v[126:129], v[18:33]
	ds_read_b128 v[130:133], v164 offset:44064
	s_waitcnt lgkmcnt(0)
	v_mfma_f32_32x32x16_bf16 v[34:49], v[130:133], v[126:129], v[34:49]
	ds_read_b128 v[130:133], v164 offset:48672
	v_mfma_f32_32x32x16_bf16 v[2:17], v[172:175], v[126:129], v[2:17]
	v_mfma_f32_32x32x16_bf16 v[82:97], v[134:137], v[126:129], v[82:97]
	s_waitcnt lgkmcnt(0)
; DI unsigned short f2bf(float f) { return (unsigned short)(cvtpk(f, 0.f) & 0xffffu); }
; DI int crow(int g, int h) { return (g & 3) + 8 * (g >> 2) + 4 * h; }
; #define MFMA32(a, b, c) __builtin_amdgcn_mfma_f32_32x32x16_bf16((a), (b), (c), 0, 0, 0)
; template <bool GLA, int MODE> ...
;     ...
; #pragma unroll
;         for (int js = 0; js < 4; ++js) {
;             const bf16x8 vb = *(const bf16x8*)(lds + S_VT + (hu * DVH + dv0 + r) * S_TS + (16 * js + 8 * hh) * 2);
;             if (MODE == 0) {
;                 if (js < 2) { const bf16x8 a0 = *(const bf16x8*)(lds + S_ATT + hu * 64 * S_TS + r * S_TS + (16 * js + 8 * hh) * 2); oa[0] = MFMA32(a0, vb, oa[0]); }
;                 { const bf16x8 a1 = *(const bf16x8*)(lds + S_ATT + hu * 64 * S_TS + (32 + r) * S_TS + (16 * js + 8 * hh) * 2); oa[1] = MFMA32(a1, vb, oa[1]); }
;             }
; #pragma unroll
;             for (int kt = 0; kt < KT; ++kt) {
;                 const bf16x8 ka = *(const bf16x8*)(lds + S_KST + (hu * DK + 32 * kt + r) * S_TS + (16 * js + 8 * hh) * 2);
;                 S[kt] = MFMA32(ka, vb, S[kt]);
;             }
;         }
; #pragma unroll
;         for (int kt = 0; kt < KT; ++kt)
; #pragma unroll
;             for (int g = 0; g < 16; ++g) S[kt][g] *= DEC[hu * DK + 32 * kt + crow(g, hh)];
;         __syncthreads();
;         if (MODE == 0) {
;             {
;                 unsigned short* OB = (unsigned short*)(lds + S_OB);
; #pragma unroll
;                 for (int it = 0; it < 2; ++it)
; #pragma unroll
;                     for (int g = 0; g < 16; ++g) OB[(32 * it + crow(g, hh)) * (S_OBS / 2) + hu * DVH + dv0 + r] = f2bf(oa[it][g]);
;             }
	v_mfma_f32_32x32x16_bf16 v[50:65], v[130:133], v[126:129], v[50:65]
	s_nop 9
	v_cvt_pk_bf16_f32 v82, v82, s0
	v_mfma_f32_32x32x16_bf16 v[66:81], v[122:125], v[126:129], v[66:81]
	ds_read_b128 v[122:125], v162 offset:53312
	ds_read_b128 v[126:129], v163 offset:4672
	ds_read_b128 v[130:133], v164 offset:34880
	s_waitcnt lgkmcnt(0)
	v_mfma_f32_32x32x16_bf16 v[2:17], v[130:133], v[122:125], v[2:17]
	ds_read_b128 v[130:133], v164 offset:39488
	s_waitcnt lgkmcnt(0)
	v_mfma_f32_32x32x16_bf16 v[18:33], v[130:133], v[122:125], v[18:33]
	ds_read_b128 v[130:133], v164 offset:44096
	s_waitcnt lgkmcnt(0)
	v_mfma_f32_32x32x16_bf16 v[34:49], v[130:133], v[122:125], v[34:49]
	ds_read_b128 v[130:133], v164 offset:48704
	s_waitcnt lgkmcnt(0)
	v_mfma_f32_32x32x16_bf16 v[50:65], v[130:133], v[122:125], v[50:65]
	v_mfma_f32_32x32x16_bf16 v[66:81], v[126:129], v[122:125], v[66:81]
	ds_read_b128 v[122:125], v162 offset:53344
	ds_read_b128 v[126:129], v163 offset:4704
	ds_read_b128 v[130:133], v164 offset:34912
	s_waitcnt lgkmcnt(0)
	v_mfma_f32_32x32x16_bf16 v[2:17], v[130:133], v[122:125], v[2:17]
	ds_read_b128 v[130:133], v164 offset:39520
	s_waitcnt lgkmcnt(0)
	v_mfma_f32_32x32x16_bf16 v[18:33], v[130:133], v[122:125], v[18:33]
	ds_read_b128 v[130:133], v164 offset:44128
	s_waitcnt lgkmcnt(0)
	v_mfma_f32_32x32x16_bf16 v[34:49], v[130:133], v[122:125], v[34:49]
	ds_read_b128 v[130:133], v164 offset:48736
	s_waitcnt lgkmcnt(0)
	v_mfma_f32_32x32x16_bf16 v[50:65], v[130:133], v[122:125], v[50:65]
	v_mfma_f32_32x32x16_bf16 v[66:81], v[126:129], v[122:125], v[66:81]
	ds_read_b128 v[122:125], v165
	ds_read_b128 v[126:129], v165 offset:32
	s_waitcnt lgkmcnt(1)
	v_mul_f32_e64 v2, v2, v122
	v_mul_f32_e64 v3, v3, v123
	v_pk_mul_f32 v[4:5], v[4:5], v[124:125]
	ds_read_b128 v[122:125], v165 offset:64
	s_nop 4
	v_cvt_pk_bf16_f32 v66, v66, s0
	s_waitcnt lgkmcnt(1)
	v_pk_mul_f32 v[6:7], v[6:7], v[126:127]
	v_pk_mul_f32 v[8:9], v[8:9], v[128:129]
	s_waitcnt lgkmcnt(0)
	v_pk_mul_f32 v[10:11], v[10:11], v[122:123]
	v_pk_mul_f32 v[12:13], v[12:13], v[124:125]
	ds_read_b128 v[122:125], v165 offset:96
	s_waitcnt lgkmcnt(0)
	v_pk_mul_f32 v[14:15], v[14:15], v[122:123]
	v_pk_mul_f32 v[16:17], v[16:17], v[124:125]
	ds_read_b128 v[122:125], v165 offset:128
	s_waitcnt lgkmcnt(0)
	v_pk_mul_f32 v[18:19], v[18:19], v[122:123]
	v_pk_mul_f32 v[20:21], v[20:21], v[124:125]
	ds_read_b128 v[122:125], v165 offset:160
	s_waitcnt lgkmcnt(0)
	v_pk_mul_f32 v[22:23], v[22:23], v[122:123]
	v_pk_mul_f32 v[24:25], v[24:25], v[124:125]
	ds_read_b128 v[122:125], v165 offset:192
	s_waitcnt lgkmcnt(0)
	v_pk_mul_f32 v[26:27], v[26:27], v[122:123]
	v_pk_mul_f32 v[28:29], v[28:29], v[124:125]
	ds_read_b128 v[122:125], v165 offset:224
	s_waitcnt lgkmcnt(0)
	v_pk_mul_f32 v[30:31], v[30:31], v[122:123]
	v_pk_mul_f32 v[32:33], v[32:33], v[124:125]
	ds_read_b128 v[122:125], v165 offset:256
	s_waitcnt lgkmcnt(0)
	v_pk_mul_f32 v[34:35], v[34:35], v[122:123]
	v_pk_mul_f32 v[36:37], v[36:37], v[124:125]
	ds_read_b128 v[122:125], v165 offset:288
	s_waitcnt lgkmcnt(0)
	v_pk_mul_f32 v[38:39], v[38:39], v[122:123]
	v_pk_mul_f32 v[40:41], v[40:41], v[124:125]
	ds_read_b128 v[122:125], v165 offset:320
	s_waitcnt lgkmcnt(0)
	v_pk_mul_f32 v[42:43], v[42:43], v[122:123]
	v_pk_mul_f32 v[44:45], v[44:45], v[124:125]
	ds_read_b128 v[122:125], v165 offset:352
	s_waitcnt lgkmcnt(0)
	v_pk_mul_f32 v[46:47], v[46:47], v[122:123]
	v_pk_mul_f32 v[48:49], v[48:49], v[124:125]
	ds_read_b128 v[122:125], v165 offset:384
	s_waitcnt lgkmcnt(0)
	v_pk_mul_f32 v[50:51], v[50:51], v[122:123]
	v_pk_mul_f32 v[52:53], v[52:53], v[124:125]
	ds_read_b128 v[122:125], v165 offset:416
	s_waitcnt lgkmcnt(0)
	v_pk_mul_f32 v[54:55], v[54:55], v[122:123]
	v_pk_mul_f32 v[56:57], v[56:57], v[124:125]
	ds_read_b128 v[122:125], v165 offset:448
	s_waitcnt lgkmcnt(0)
	v_pk_mul_f32 v[58:59], v[58:59], v[122:123]
	v_pk_mul_f32 v[60:61], v[60:61], v[124:125]
	ds_read_b128 v[122:125], v165 offset:480
	s_waitcnt lgkmcnt(0)
	s_barrier
	ds_write_b16 v166, v66 offset:16896
	v_cvt_pk_bf16_f32 v66, v67, s0
	ds_write_b16 v166, v66 offset:17424
	v_cvt_pk_bf16_f32 v66, v68, s0
	ds_write_b16 v166, v66 offset:17952
	v_cvt_pk_bf16_f32 v66, v69, s0
	ds_write_b16 v166, v66 offset:18480
	v_cvt_pk_bf16_f32 v66, v70, s0
	ds_write_b16 v166, v66 offset:21120
	v_cvt_pk_bf16_f32 v66, v71, s0
	ds_write_b16 v166, v66 offset:21648
	v_cvt_pk_bf16_f32 v66, v72, s0
	ds_write_b16 v166, v66 offset:22176
	v_cvt_pk_bf16_f32 v66, v73, s0
	ds_write_b16 v166, v66 offset:22704
	v_cvt_pk_bf16_f32 v66, v74, s0
	ds_write_b16 v166, v66 offset:25344
	v_cvt_pk_bf16_f32 v66, v75, s0
	ds_write_b16 v166, v82
	v_cvt_pk_bf16_f32 v82, v83, s0
	ds_write_b16 v166, v66 offset:25872
	v_cvt_pk_bf16_f32 v66, v76, s0
	ds_write_b16 v166, v82 offset:528
	v_cvt_pk_bf16_f32 v82, v84, s0
	ds_write_b16 v166, v66 offset:26400
	v_cvt_pk_bf16_f32 v66, v77, s0
	ds_write_b16 v166, v82 offset:1056
	v_cvt_pk_bf16_f32 v82, v85, s0
	ds_write_b16 v166, v66 offset:26928
	v_cvt_pk_bf16_f32 v66, v78, s0
	ds_write_b16 v166, v82 offset:1584
	v_cvt_pk_bf16_f32 v82, v86, s0
	ds_write_b16 v166, v66 offset:29568
	v_cvt_pk_bf16_f32 v66, v79, s0
	ds_write_b16 v166, v82 offset:4224
	v_cvt_pk_bf16_f32 v82, v87, s0
	ds_write_b16 v166, v66 offset:30096
	v_cvt_pk_bf16_f32 v66, v80, s0
	ds_write_b16 v166, v82 offset:4752
	v_cvt_pk_bf16_f32 v82, v88, s0
	ds_write_b16 v166, v66 offset:30624
	v_cvt_pk_bf16_f32 v66, v81, s0
	v_and_b32_e32 v67, 64, v220
	ds_write_b16 v166, v82 offset:5280
	v_cvt_pk_bf16_f32 v82, v89, s0
	ds_write_b16 v166, v66 offset:31152
	v_xor_b32_e32 v66, 1, v220
	v_add_u32_e32 v67, 64, v67
	ds_write_b16 v166, v82 offset:5808
	v_cvt_pk_bf16_f32 v82, v90, s0
	v_cmp_lt_i32_e32 vcc, v66, v67
	ds_write_b16 v166, v82 offset:8448
	v_cvt_pk_bf16_f32 v82, v91, s0
	v_cndmask_b32_e32 v66, v220, v66, vcc
	ds_write_b16 v166, v82 offset:8976
	v_cvt_pk_bf16_f32 v82, v92, s0
	v_lshlrev_b32_e32 v194, 2, v66
	v_xor_b32_e32 v66, 2, v220
	ds_write_b16 v166, v82 offset:9504
	v_cvt_pk_bf16_f32 v82, v93, s0
	v_cmp_lt_i32_e32 vcc, v66, v67
	ds_write_b16 v166, v82 offset:10032
	v_cvt_pk_bf16_f32 v82, v94, s0
	v_cndmask_b32_e32 v66, v220, v66, vcc
	ds_write_b16 v166, v82 offset:12672
	v_cvt_pk_bf16_f32 v82, v95, s0
	v_lshlrev_b32_e32 v195, 2, v66
	v_xor_b32_e32 v66, 4, v220
	ds_write_b16 v166, v82 offset:13200
	v_cvt_pk_bf16_f32 v82, v96, s0
	v_cmp_lt_i32_e32 vcc, v66, v67
	ds_write_b16 v166, v82 offset:13728
	v_cvt_pk_bf16_f32 v82, v97, s0
	v_cndmask_b32_e32 v66, v220, v66, vcc
	ds_write_b16 v166, v82 offset:14256
	s_waitcnt lgkmcnt(0)
	s_barrier
; DI float bflo(unsigned w) { return __uint_as_float(w << 16); }
; DI float bfhi(unsigned w) { return __uint_as_float(w & 0xffff0000u); }
; template <bool GLA, int MODE> ...
;     ...
;             {
;                 const int i = tid >> 3, p = tid & 7;
;                 const u32x4* src = (const u32x4*)(lds + S_OB + i * S_OBS + p * 64);
;                 float x[32];
; #pragma unroll
;                 for (int q = 0; q < 4; ++q) { const u32x4 w = src[q];
;                     x[8 * q + 0] = bflo(w.x); x[8 * q + 1] = bfhi(w.x); x[8 * q + 2] = bflo(w.y); x[8 * q + 3] = bfhi(w.y);
;                     x[8 * q + 4] = bflo(w.z); x[8 * q + 5] = bfhi(w.z); x[8 * q + 6] = bflo(w.w); x[8 * q + 7] = bfhi(w.w); }
;                 float s = 0.f;
;                 if (!GLA) {
; #pragma unroll
;                     for (int q = 0; q < 32; ++q) s += x[q];
;                     s += __shfl_xor(s, 1); s += __shfl_xor(s, 2);
;                     const float mean = s * (1.f / 128.f);
; #pragma unroll
;                     for (int q = 0; q < 32; ++q) x[q] -= mean;
;                 }
;                 float s2 = 0.f;
; #pragma unroll
;                 for (int q = 0; q < 32; ++q) s2 += x[q] * x[q];
;                 s2 += __shfl_xor(s2, 1); s2 += __shfl_xor(s2, 2); if (GLA) s2 += __shfl_xor(s2, 4);
	ds_read_b128 v[80:83], v167
	ds_read_b128 v[126:129], v167 offset:16
	ds_read_b128 v[130:133], v167 offset:32
	ds_read_b128 v[134:137], v167 offset:48
	v_lshlrev_b32_e32 v196, 2, v66
	v_add_u32_e32 v66, s8, v154
	v_ashrrev_i32_e32 v67, 31, v66
	v_lshlrev_b64 v[66:67], 11, v[66:67]
	s_waitcnt lgkmcnt(3)
	v_lshlrev_b32_e32 v176, 16, v80
	v_and_b32_e32 v177, 0xffff0000, v80
	v_pk_mul_f32 v[64:65], v[64:65], v[124:125]
	v_lshl_add_u64 v[78:79], v[146:147], 0, v[66:67]
	global_load_dwordx4 v[66:69], v[144:145], off offset:16
	global_load_dwordx4 v[70:73], v[144:145], off
	global_load_dwordx4 v[198:201], v[144:145], off offset:48
	global_load_dwordx4 v[202:205], v[144:145], off offset:32
	global_load_dwordx4 v[206:209], v[144:145], off offset:80
	global_load_dwordx4 v[226:229], v[144:145], off offset:64
	global_load_dwordx4 v[230:233], v[144:145], off offset:112
	global_load_dwordx4 v[234:237], v[144:145], off offset:96
	v_lshlrev_b32_e32 v124, 16, v81
	v_and_b32_e32 v125, 0xffff0000, v81
	v_pk_mul_f32 v[178:179], v[176:177], v[176:177]
	v_pk_mul_f32 v[174:175], v[124:125], v[124:125]
	v_add_f32_e32 v178, v178, v179
	v_lshlrev_b32_e32 v96, 16, v82
	v_and_b32_e32 v97, 0xffff0000, v82
	v_add_f32_e32 v174, v174, v178
	v_pk_mul_f32 v[172:173], v[96:97], v[96:97]
	v_add_f32_e32 v174, v175, v174
	v_lshlrev_b32_e32 v92, 16, v83
	v_and_b32_e32 v93, 0xffff0000, v83
	v_add_f32_e32 v172, v172, v174
	v_pk_mul_f32 v[170:171], v[92:93], v[92:93]
	v_add_f32_e32 v172, v173, v172
	s_waitcnt lgkmcnt(2)
	v_lshlrev_b32_e32 v184, 16, v126
	v_and_b32_e32 v185, 0xffff0000, v126
	v_add_f32_e32 v170, v170, v172
	v_pk_mul_f32 v[62:63], v[62:63], v[122:123]
	v_lshlrev_b32_e32 v122, 16, v127
	v_and_b32_e32 v123, 0xffff0000, v127
	v_pk_mul_f32 v[126:127], v[184:185], v[184:185]
	v_add_f32_e32 v170, v171, v170
	v_add_f32_e32 v126, v126, v170
	v_pk_mul_f32 v[182:183], v[122:123], v[122:123]
	v_add_f32_e32 v126, v127, v126
	v_lshlrev_b32_e32 v90, 16, v128
	v_and_b32_e32 v91, 0xffff0000, v128
	v_add_f32_e32 v126, v182, v126
	v_lshlrev_b32_e32 v86, 16, v129
	v_and_b32_e32 v87, 0xffff0000, v129
	v_pk_mul_f32 v[128:129], v[90:91], v[90:91]
	v_add_f32_e32 v126, v183, v126
	v_add_f32_e32 v126, v128, v126
	v_pk_mul_f32 v[180:181], v[86:87], v[86:87]
	v_add_f32_e32 v126, v129, v126
	s_waitcnt lgkmcnt(1)
	v_lshlrev_b32_e32 v190, 16, v130
	v_and_b32_e32 v191, 0xffff0000, v130
	v_add_f32_e32 v126, v180, v126
	v_lshlrev_b32_e32 v88, 16, v131
	v_and_b32_e32 v89, 0xffff0000, v131
	v_pk_mul_f32 v[130:131], v[190:191], v[190:191]
	v_add_f32_e32 v126, v181, v126
	v_add_f32_e32 v126, v130, v126
	v_pk_mul_f32 v[188:189], v[88:89], v[88:89]
	v_add_f32_e32 v126, v131, v126
	v_lshlrev_b32_e32 v82, 16, v132
	v_and_b32_e32 v83, 0xffff0000, v132
	v_add_f32_e32 v126, v188, v126
	v_lshlrev_b32_e32 v80, 16, v133
	v_and_b32_e32 v81, 0xffff0000, v133
	v_pk_mul_f32 v[132:133], v[82:83], v[82:83]
	v_add_f32_e32 v126, v189, v126
	v_add_f32_e32 v126, v132, v126
	v_pk_mul_f32 v[186:187], v[80:81], v[80:81]
	v_add_f32_e32 v126, v133, v126
	s_waitcnt lgkmcnt(0)
	v_lshlrev_b32_e32 v94, 16, v134
	v_and_b32_e32 v95, 0xffff0000, v134
	v_add_f32_e32 v126, v186, v126
	v_lshlrev_b32_e32 v84, 16, v135
	v_and_b32_e32 v85, 0xffff0000, v135
	v_pk_mul_f32 v[134:135], v[94:95], v[94:95]
	v_add_f32_e32 v126, v187, v126
	v_add_f32_e32 v126, v134, v126
	v_pk_mul_f32 v[192:193], v[84:85], v[84:85]
	v_add_f32_e32 v126, v135, v126
	v_and_b32_e32 v74, 0xffff0000, v136
	v_lshlrev_b32_e32 v75, 16, v136
	v_add_f32_e32 v126, v192, v126
	v_pk_mul_f32 v[168:169], v[74:75], v[74:75]
	v_add_f32_e32 v126, v193, v126
	v_and_b32_e32 v76, 0xffff0000, v137
	v_lshlrev_b32_e32 v77, 16, v137
	v_add_f32_e32 v126, v169, v126
	v_pk_mul_f32 v[136:137], v[76:77], v[76:77]
	v_add_f32_e32 v126, v168, v126
	v_add_f32_e32 v126, v137, v126
	v_add_f32_e32 v126, v136, v126
	ds_bpermute_b32 v127, v194, v126
	s_mov_b32 s8, 0xf800000
	s_waitcnt lgkmcnt(0)
; DI unsigned cvtpk(float lo, float hi) { f32x2_t v = {lo, hi}; bf16x2_t b = __builtin_convertvector(v, bf16x2_t); return __builtin_bit_cast(unsigned, b); }
; template <bool GLA, int MODE> ...
;     ...
;                 s2 += __shfl_xor(s2, 1); s2 += __shfl_xor(s2, 2); if (GLA) s2 += __shfl_xor(s2, 4);
;                 const float rstd = 1.f / sqrtf(s2 * (1.f / DVH) + EPS);
;                 const float* gp = gain + 32 * p;
;                 u32x4* dst = (u32x4*)(OUT + (size_t)(row0 + i) * out_ld + ocol0 + 32 * p);
; #pragma unroll
;                 for (int q = 0; q < 4; ++q) {
;                     u32x4 w;
;                     w.x = cvtpk(x[8 * q + 0] * rstd * gp[8 * q + 0], x[8 * q + 1] * rstd * gp[8 * q + 1]);
;                     w.y = cvtpk(x[8 * q + 2] * rstd * gp[8 * q + 2], x[8 * q + 3] * rstd * gp[8 * q + 3]);
;                     w.z = cvtpk(x[8 * q + 4] * rstd * gp[8 * q + 4], x[8 * q + 5] * rstd * gp[8 * q + 5]);
;                     w.w = cvtpk(x[8 * q + 6] * rstd * gp[8 * q + 6], x[8 * q + 7] * rstd * gp[8 * q + 7]);
;                     dst[q] = w;
;                 }
	v_add_f32_e32 v126, v126, v127
	ds_bpermute_b32 v127, v195, v126
	s_waitcnt lgkmcnt(0)
	v_add_f32_e32 v126, v126, v127
	ds_bpermute_b32 v127, v196, v126
	s_waitcnt lgkmcnt(0)
	v_add_f32_e32 v126, v126, v127
	v_fmamk_f32 v126, v126, 0x3b800000, v214
	v_cmp_gt_f32_e32 vcc, s8, v126
	v_mul_f32_e32 v127, 0x4f800000, v126
	s_nop 0
	v_cndmask_b32_e32 v126, v126, v127, vcc
	v_sqrt_f32_e32 v127, v126
	s_nop 0
	v_add_u32_e32 v128, -1, v127
	v_fma_f32 v129, -v128, v127, v126
	v_cmp_ge_f32_e64 s[86:87], 0, v129
	v_add_u32_e32 v129, 1, v127
	s_nop 0
	v_cndmask_b32_e64 v128, v127, v128, s[86:87]
	v_fma_f32 v127, -v129, v127, v126
	v_cmp_lt_f32_e64 s[86:87], 0, v127
	s_nop 1
	v_cndmask_b32_e64 v127, v128, v129, s[86:87]
	v_mul_f32_e32 v128, 0x37800000, v127
	v_cndmask_b32_e32 v127, v127, v128, vcc
	v_cmp_class_f32_e32 vcc, v126, v215
	s_nop 1
	v_cndmask_b32_e32 v126, v127, v126, vcc
	v_div_scale_f32 v127, s[8:9], v126, v126, 1.0
	v_rcp_f32_e32 v128, v127
	s_nop 0
	v_fma_f32 v129, -v127, v128, 1.0
	v_fmac_f32_e32 v128, v129, v128
	v_div_scale_f32 v129, vcc, 1.0, v126, 1.0
	v_mul_f32_e32 v130, v129, v128
	v_fma_f32 v131, -v127, v130, v129
	v_fmac_f32_e32 v130, v131, v128
	v_fma_f32 v127, -v127, v130, v129
	v_div_fmas_f32 v127, v127, v128, v130
	v_div_fixup_f32 v126, v127, v126, 1.0
	v_pk_mul_f32 v[128:129], v[126:127], v[176:177] op_sel_hi:[0,1]
	v_pk_mul_f32 v[124:125], v[126:127], v[124:125] op_sel_hi:[0,1]
	s_waitcnt vmcnt(0)
	v_pk_mul_f32 v[70:71], v[70:71], v[128:129]
	v_pk_mul_f32 v[72:73], v[72:73], v[124:125]
	v_cvt_pk_bf16_f32 v70, v70, v71
	v_cvt_pk_bf16_f32 v71, v72, v73
	v_pk_mul_f32 v[72:73], v[126:127], v[96:97] op_sel_hi:[0,1]
	v_pk_mul_f32 v[66:67], v[66:67], v[72:73]
	s_nop 0
	v_cvt_pk_bf16_f32 v72, v66, v67
	v_pk_mul_f32 v[66:67], v[126:127], v[92:93] op_sel_hi:[0,1]
	v_pk_mul_f32 v[66:67], v[68:69], v[66:67]
	v_pk_mul_f32 v[92:93], v[126:127], v[184:185] op_sel_hi:[0,1]
	v_cvt_pk_bf16_f32 v73, v66, v67
	global_store_dwordx4 v[78:79], v[70:73], off
	s_nop 1
	v_pk_mul_f32 v[70:71], v[202:203], v[92:93]
	v_pk_mul_f32 v[92:93], v[126:127], v[122:123] op_sel_hi:[0,1]
	v_pk_mul_f32 v[72:73], v[204:205], v[92:93]
	v_cvt_pk_bf16_f32 v70, v70, v71
	v_cvt_pk_bf16_f32 v71, v72, v73
	v_pk_mul_f32 v[72:73], v[126:127], v[90:91] op_sel_hi:[0,1]
	v_pk_mul_f32 v[66:67], v[198:199], v[72:73]
	s_nop 0
	v_cvt_pk_bf16_f32 v72, v66, v67
	v_pk_mul_f32 v[66:67], v[126:127], v[86:87] op_sel_hi:[0,1]
	v_pk_mul_f32 v[66:67], v[200:201], v[66:67]
	v_pk_mul_f32 v[86:87], v[126:127], v[190:191] op_sel_hi:[0,1]
	v_cvt_pk_bf16_f32 v73, v66, v67
	global_store_dwordx4 v[78:79], v[70:73], off offset:16
	s_nop 1
	v_pk_mul_f32 v[70:71], v[226:227], v[86:87]
	v_pk_mul_f32 v[86:87], v[126:127], v[88:89] op_sel_hi:[0,1]
	v_pk_mul_f32 v[72:73], v[228:229], v[86:87]
	v_cvt_pk_bf16_f32 v70, v70, v71
	v_cvt_pk_bf16_f32 v71, v72, v73
	v_pk_mul_f32 v[72:73], v[126:127], v[82:83] op_sel_hi:[0,1]
	v_pk_mul_f32 v[66:67], v[206:207], v[72:73]
	s_nop 0
	v_cvt_pk_bf16_f32 v72, v66, v67
	v_pk_mul_f32 v[66:67], v[126:127], v[80:81] op_sel_hi:[0,1]
	v_pk_mul_f32 v[66:67], v[208:209], v[66:67]
	v_pk_mul_f32 v[80:81], v[126:127], v[94:95] op_sel_hi:[0,1]
	v_cvt_pk_bf16_f32 v73, v66, v67
	global_store_dwordx4 v[78:79], v[70:73], off offset:32
	s_nop 1
	v_pk_mul_f32 v[70:71], v[234:235], v[80:81]
	v_pk_mul_f32 v[80:81], v[126:127], v[84:85] op_sel_hi:[0,1]
	v_pk_mul_f32 v[72:73], v[236:237], v[80:81]
	v_cvt_pk_bf16_f32 v70, v70, v71
	v_cvt_pk_bf16_f32 v71, v72, v73
	v_pk_mul_f32 v[72:73], v[126:127], v[74:75] op_sel_hi:[0,1]
	v_pk_mul_f32 v[66:67], v[230:231], v[72:73] op_sel:[0,1] op_sel_hi:[1,0]
	s_nop 0
	v_cvt_pk_bf16_f32 v72, v66, v67
	v_pk_mul_f32 v[66:67], v[126:127], v[76:77] op_sel_hi:[0,1]
	v_pk_mul_f32 v[66:67], v[232:233], v[66:67] op_sel:[0,1] op_sel_hi:[1,0]
	s_nop 0
	v_cvt_pk_bf16_f32 v73, v66, v67
	global_store_dwordx4 v[78:79], v[70:73], off offset:48
	s_barrier
	s_cbranch_scc1 .LBB0_1690

; template <bool GLA, int MODE> ...
;     ...
;         { const bf16_t* cb_ = PST + (size_t)cidx * NIN_SCAN * 64;
; #pragma unroll
;           for (int i_ = 0; i_ < 4; ++i_) vv[i_] = *(const u32x4*)(cb_ + ((size_t)i_ * NIN_SCAN + vcol0) * 16 + (size_t)tid * 8); }
;         float bl[16]; float run = 0.f;
; #pragma unroll
;         for (int j = 0; j < 16; ++j) {
;             float la;
;             if (GLA) {
;                 const unsigned w = law[j >> 3][(j >> 1) & 3];
;                 la = (float)__builtin_bit_cast(_Float16, (unsigned short)((j & 1) ? (w >> 16) : (w & 0xffffu)));
;             } else la = lgc;
;             run += la; bl[j] = run;
;         }
;         GSUM[rg * 128 + dcol] = run;
.LBB0_1684:
	v_lshl_add_u64 v[66:67], v[150:151], 0, vcc
	v_add_co_u32_e32 v68, vcc, 0x10000, v66
	s_nop 1
	v_addc_co_u32_e32 v69, vcc, 0, v67, vcc
	v_add_co_u32_e32 v70, vcc, 0x28000, v66
	s_nop 1
	v_addc_co_u32_e32 v71, vcc, 0, v67, vcc
	global_load_dwordx4 v[122:125], v[68:69], off
	global_load_dwordx4 v[126:129], v[70:71], off
	v_add_co_u32_e32 v68, vcc, 0x40000, v66
	s_waitcnt vmcnt(2)
	v_cvt_f32_f16_e32 v70, v117
	v_addc_co_u32_e32 v69, vcc, 0, v67, vcc
	v_add_co_u32_e32 v66, vcc, 0x58000, v66
	v_cvt_f32_f16_sdwa v71, v117 dst_sel:DWORD dst_unused:UNUSED_PAD src0_sel:WORD_1
	s_nop 0
	v_addc_co_u32_e32 v67, vcc, 0, v67, vcc
	global_load_dwordx4 v[130:133], v[68:69], off
	global_load_dwordx4 v[134:137], v[66:67], off
	v_cvt_f32_f16_e32 v66, v114
	v_cvt_f32_f16_sdwa v67, v114 dst_sel:DWORD dst_unused:UNUSED_PAD src0_sel:WORD_1
	v_cvt_f32_f16_e32 v68, v115
	v_cvt_f32_f16_sdwa v69, v115 dst_sel:DWORD dst_unused:UNUSED_PAD src0_sel:WORD_1
	v_add_f32_e32 v66, 0, v66
	v_add_f32_e32 v67, v66, v67
	v_add_f32_e32 v74, v67, v68
	v_cvt_f32_f16_e32 v68, v116
	v_add_f32_e32 v75, v74, v69
	v_cvt_f32_f16_sdwa v69, v116 dst_sel:DWORD dst_unused:UNUSED_PAD src0_sel:WORD_1
	v_add_f32_e32 v76, v75, v68
	v_cvt_f32_f16_e32 v68, v118
	v_add_f32_e32 v77, v76, v69
	v_cvt_f32_f16_sdwa v69, v118 dst_sel:DWORD dst_unused:UNUSED_PAD src0_sel:WORD_1
	v_add_f32_e32 v78, v77, v70
	v_cvt_f32_f16_e32 v70, v119
	v_add_f32_e32 v79, v78, v71
	v_cvt_f32_f16_sdwa v71, v119 dst_sel:DWORD dst_unused:UNUSED_PAD src0_sel:WORD_1
	v_add_f32_e32 v80, v79, v68
	v_cvt_f32_f16_e32 v68, v120
	v_add_f32_e32 v81, v80, v69
	v_cvt_f32_f16_sdwa v69, v120 dst_sel:DWORD dst_unused:UNUSED_PAD src0_sel:WORD_1
	v_add_f32_e32 v82, v81, v70
	v_cvt_f32_f16_e32 v70, v121
	v_add_f32_e32 v83, v82, v71
	v_cvt_f32_f16_sdwa v71, v121 dst_sel:DWORD dst_unused:UNUSED_PAD src0_sel:WORD_1
	v_add_f32_e32 v84, v83, v68
	v_add_f32_e32 v85, v84, v69
	v_add_f32_e32 v86, v85, v70
	v_add_f32_e32 v87, v86, v71
	ds_write_b32 v139, v87
	s_waitcnt lgkmcnt(0)
	s_barrier
; DI unsigned cvtpk(float lo, float hi) { f32x2_t v = {lo, hi}; bf16x2_t b = __builtin_convertvector(v, bf16x2_t); return __builtin_bit_cast(unsigned, b); }
; DI unsigned short f2bf(float f) { return (unsigned short)(cvtpk(f, 0.f) & 0xffffu); }
; DI float bflo(unsigned w) { return __uint_as_float(w << 16); }
; DI float bfhi(unsigned w) { return __uint_as_float(w & 0xffff0000u); }
; template <bool GLA, int MODE> ...
;     ...
;         {
;             float pre = 0.f, tot = 0.f;
; #pragma unroll
;             for (int g = 0; g < 4; ++g) { const float t = GSUM[g * 128 + dcol]; tot += t; if (g < rg) pre += t; }
;             ldtot += tot;
;             unsigned ksw[8];
; #pragma unroll
;             for (int j = 0; j < 16; j += 2) {
;                 const unsigned kw = kraw[j >> 3][(j >> 1) & 3];
;                 const float b0 = pre + bl[j], b1 = pre + bl[j + 1];
;                 const float k0 = bflo(kw), k1 = bfhi(kw);
;                 const unsigned kew = cvtpk(k0 * __expf(-b0), k1 * __expf(-b1));
;                 if (MODE == 0) {
;                     const unsigned qw = qraw[j >> 3][(j >> 1) & 3];
;                     const float q0 = bflo(qw), q1 = bfhi(qw);
;                     QE[(16 * rg + j) * (S_QES / 2) + dcol] = f2bf(q0 * __expf(b0)); QE[(16 * rg + j + 1) * (S_QES / 2) + dcol] = f2bf(q1 * __expf(b1));
;                     KE[(16 * rg + j) * (S_QES / 2) + dcol] = (unsigned short)(kew & 0xffffu); KE[(16 * rg + j + 1) * (S_QES / 2) + dcol] = (unsigned short)(kew >> 16);
;                 }
;                 ksw[j >> 1] = kew;
;             }
;             u32x4* kp = (u32x4*)(lds + S_KST + dcol * S_TS + 32 * rg);
;             kp[0] = (u32x4){ksw[0], ksw[1], ksw[2], ksw[3]}; kp[1] = (u32x4){ksw[4], ksw[5], ksw[6], ksw[7]};
;             if (rg == 0) DEC[dcol] = __expf(tot);
	ds_read2st64_b32 v[70:71], v141 offset1:2
	ds_read2st64_b32 v[72:73], v141 offset0:4 offset1:6
	s_waitcnt lgkmcnt(1)
	v_add_f32_e32 v70, 0, v70
	v_cndmask_b32_e64 v68, 0, v70, s[44:45]
	v_add_f32_e32 v69, v71, v68
	v_cndmask_b32_e64 v68, v68, v69, s[46:47]
	s_waitcnt lgkmcnt(0)
	v_add_f32_e32 v69, v72, v68
	v_cndmask_b32_e64 v68, v68, v69, s[48:49]
	v_add_f32_e32 v69, v73, v68
	v_cndmask_b32_e64 v88, v68, v69, s[50:51]
	v_add_f32_e32 v89, v66, v88
	v_add_f32_e32 v90, v67, v88
	v_mul_f32_e32 v66, 0xbfb8aa3b, v89
	v_mul_f32_e32 v67, 0xbfb8aa3b, v90
	v_exp_f32_e32 v66, v66
	v_exp_f32_e32 v67, v67
	v_lshlrev_b32_e32 v68, 16, v102
	v_and_b32_e32 v69, 0xffff0000, v102
	v_add_f32_e32 v76, v76, v88
	v_pk_mul_f32 v[66:67], v[66:67], v[68:69]
	v_mul_f32_e32 v68, 0x3fb8aa3b, v89
	v_exp_f32_e32 v68, v68
	v_mul_f32_e32 v89, 0x3fb8aa3b, v90
	v_exp_f32_e32 v89, v89
	v_cvt_pk_bf16_f32 v66, v66, v67
	v_lshlrev_b32_e32 v67, 16, v110
	v_mul_f32_e32 v67, v68, v67
	v_and_b32_e32 v69, 0xffff0000, v110
	v_cvt_pk_bf16_f32 v67, v67, s0
	ds_write_b16 v155, v67
	v_mul_f32_e32 v67, v89, v69
	v_cvt_pk_bf16_f32 v67, v67, s0
	v_add_f32_e32 v89, v74, v88
	ds_write_b16 v155, v67 offset:272
	ds_write_b16 v155, v66 offset:17408
	v_add_f32_e32 v90, v75, v88
	v_mul_f32_e32 v67, 0xbfb8aa3b, v89
	v_exp_f32_e32 v68, v67
	v_mul_f32_e32 v67, 0xbfb8aa3b, v90
	v_exp_f32_e32 v69, v67
	v_lshlrev_b32_e32 v74, 16, v103
	v_and_b32_e32 v75, 0xffff0000, v103
	v_add_f32_e32 v77, v77, v88
	v_pk_mul_f32 v[68:69], v[68:69], v[74:75]
	v_mul_f32_e32 v75, 0x3fb8aa3b, v90
	v_cvt_pk_bf16_f32 v67, v68, v69
	v_mul_f32_e32 v69, 0x3fb8aa3b, v89
	v_exp_f32_e32 v69, v69
	v_exp_f32_e32 v75, v75
	v_lshlrev_b32_e32 v68, 16, v111
	v_and_b32_e32 v74, 0xffff0000, v111
	v_mul_f32_e32 v68, v69, v68
	v_cvt_pk_bf16_f32 v68, v68, s0
	ds_write_b16 v155, v68 offset:544
	v_mul_f32_e32 v68, v75, v74
	v_cvt_pk_bf16_f32 v68, v68, s0
	ds_write_b16_d16_hi v155, v66 offset:17680
	ds_write_b16 v155, v68 offset:816
	ds_write_b16 v155, v67 offset:17952
	v_mul_f32_e32 v68, 0xbfb8aa3b, v76
	v_mul_f32_e32 v69, 0xbfb8aa3b, v77
	v_exp_f32_e32 v68, v68
	v_exp_f32_e32 v69, v69
	v_lshlrev_b32_e32 v74, 16, v104
	v_and_b32_e32 v75, 0xffff0000, v104
	v_add_f32_e32 v78, v78, v88
	v_pk_mul_f32 v[68:69], v[68:69], v[74:75]
	v_mul_f32_e32 v74, 0x3fb8aa3b, v76
	v_exp_f32_e32 v74, v74
	v_mul_f32_e32 v76, 0x3fb8aa3b, v77
	v_exp_f32_e32 v76, v76
	v_cvt_pk_bf16_f32 v68, v68, v69
	v_lshlrev_b32_e32 v69, 16, v112
	v_mul_f32_e32 v69, v74, v69
	v_and_b32_e32 v75, 0xffff0000, v112
	v_cvt_pk_bf16_f32 v69, v69, s0
	ds_write_b16 v155, v69 offset:1088
	v_mul_f32_e32 v69, v76, v75
	v_cvt_pk_bf16_f32 v69, v69, s0
	ds_write_b16_d16_hi v155, v67 offset:18224
	ds_write_b16 v155, v69 offset:1360
	ds_write_b16 v155, v68 offset:18496
	v_add_f32_e32 v79, v79, v88
	v_mul_f32_e32 v69, 0xbfb8aa3b, v78
	v_exp_f32_e32 v74, v69
	v_mul_f32_e32 v69, 0xbfb8aa3b, v79
	v_exp_f32_e32 v75, v69
	v_lshlrev_b32_e32 v76, 16, v105
	v_and_b32_e32 v77, 0xffff0000, v105
	ds_write_b16_d16_hi v155, v68 offset:18768
	v_pk_mul_f32 v[74:75], v[74:75], v[76:77]
	v_mul_f32_e32 v77, 0x3fb8aa3b, v79
	v_cvt_pk_bf16_f32 v69, v74, v75
	v_mul_f32_e32 v75, 0x3fb8aa3b, v78
	v_exp_f32_e32 v75, v75
	v_exp_f32_e32 v77, v77
	v_lshlrev_b32_e32 v74, 16, v113
	v_and_b32_e32 v76, 0xffff0000, v113
	v_mul_f32_e32 v74, v75, v74
	v_cvt_pk_bf16_f32 v74, v74, s0
	ds_write_b16 v155, v74 offset:1632
	v_mul_f32_e32 v74, v77, v76
	v_cvt_pk_bf16_f32 v74, v74, s0
	v_add_f32_e32 v78, v80, v88
	v_add_f32_e32 v79, v81, v88
	ds_write_b16 v155, v74 offset:1904
	ds_write_b16 v155, v69 offset:19040
	v_mul_f32_e32 v74, 0xbfb8aa3b, v78
	v_mul_f32_e32 v75, 0xbfb8aa3b, v79
	v_exp_f32_e32 v74, v74
	v_exp_f32_e32 v75, v75
	v_lshlrev_b32_e32 v76, 16, v98
	v_and_b32_e32 v77, 0xffff0000, v98
	v_add_f32_e32 v80, v82, v88
	v_pk_mul_f32 v[74:75], v[74:75], v[76:77]
	v_mul_f32_e32 v76, 0x3fb8aa3b, v78
	v_exp_f32_e32 v76, v76
	v_mul_f32_e32 v78, 0x3fb8aa3b, v79
	v_exp_f32_e32 v78, v78
	v_cvt_pk_bf16_f32 v74, v74, v75
	v_lshlrev_b32_e32 v75, 16, v106
	v_mul_f32_e32 v75, v76, v75
	v_and_b32_e32 v77, 0xffff0000, v106
	v_cvt_pk_bf16_f32 v75, v75, s0
	ds_write_b16 v155, v75 offset:2176
	v_mul_f32_e32 v75, v78, v77
	v_cvt_pk_bf16_f32 v75, v75, s0
	ds_write_b16_d16_hi v155, v69 offset:19312
	ds_write_b16 v155, v75 offset:2448
	ds_write_b16 v155, v74 offset:19584
	v_add_f32_e32 v81, v83, v88
	v_mul_f32_e32 v75, 0xbfb8aa3b, v80
	v_exp_f32_e32 v76, v75
	v_mul_f32_e32 v75, 0xbfb8aa3b, v81
	v_exp_f32_e32 v77, v75
	v_lshlrev_b32_e32 v78, 16, v99
	v_and_b32_e32 v79, 0xffff0000, v99
	ds_write_b16_d16_hi v155, v74 offset:19856
	v_pk_mul_f32 v[76:77], v[76:77], v[78:79]
	v_mul_f32_e32 v79, 0x3fb8aa3b, v81
	v_cvt_pk_bf16_f32 v75, v76, v77
	v_mul_f32_e32 v77, 0x3fb8aa3b, v80
	v_exp_f32_e32 v77, v77
	v_exp_f32_e32 v79, v79
	v_lshlrev_b32_e32 v76, 16, v107
	v_and_b32_e32 v78, 0xffff0000, v107
	v_mul_f32_e32 v76, v77, v76
	v_cvt_pk_bf16_f32 v76, v76, s0
	ds_write_b16 v155, v76 offset:2720
	v_mul_f32_e32 v76, v79, v78
	v_cvt_pk_bf16_f32 v76, v76, s0
	v_add_f32_e32 v80, v84, v88
	v_add_f32_e32 v81, v85, v88
	ds_write_b16 v155, v76 offset:2992
	ds_write_b16 v155, v75 offset:20128
	v_mul_f32_e32 v76, 0xbfb8aa3b, v80
	v_mul_f32_e32 v77, 0xbfb8aa3b, v81
	v_exp_f32_e32 v76, v76
	v_exp_f32_e32 v77, v77
	v_lshlrev_b32_e32 v78, 16, v100
	v_and_b32_e32 v79, 0xffff0000, v100
	v_add_f32_e32 v82, v86, v88
	v_pk_mul_f32 v[76:77], v[76:77], v[78:79]
	v_mul_f32_e32 v78, 0x3fb8aa3b, v80
	v_exp_f32_e32 v78, v78
	v_mul_f32_e32 v80, 0x3fb8aa3b, v81
	v_exp_f32_e32 v80, v80
	v_cvt_pk_bf16_f32 v76, v76, v77
	v_lshlrev_b32_e32 v77, 16, v108
	v_mul_f32_e32 v77, v78, v77
	v_and_b32_e32 v79, 0xffff0000, v108
	v_cvt_pk_bf16_f32 v77, v77, s0
	ds_write_b16 v155, v77 offset:3264
	v_mul_f32_e32 v77, v80, v79
	v_cvt_pk_bf16_f32 v77, v77, s0
	ds_write_b16_d16_hi v155, v75 offset:20400
	ds_write_b16 v155, v77 offset:3536
	ds_write_b16 v155, v76 offset:20672
	v_add_f32_e32 v83, v87, v88
	v_mul_f32_e32 v77, 0xbfb8aa3b, v82
	v_exp_f32_e32 v78, v77
	v_mul_f32_e32 v77, 0xbfb8aa3b, v83
	v_exp_f32_e32 v79, v77
	v_lshlrev_b32_e32 v80, 16, v101
	v_and_b32_e32 v81, 0xffff0000, v101
	ds_write_b16_d16_hi v155, v76 offset:20944
	v_pk_mul_f32 v[78:79], v[78:79], v[80:81]
	v_mul_f32_e32 v81, 0x3fb8aa3b, v83
	v_cvt_pk_bf16_f32 v77, v78, v79
	v_mul_f32_e32 v79, 0x3fb8aa3b, v82
	v_exp_f32_e32 v79, v79
	v_exp_f32_e32 v81, v81
	v_lshlrev_b32_e32 v78, 16, v109
	v_and_b32_e32 v80, 0xffff0000, v109
	v_mul_f32_e32 v78, v79, v78
	v_cvt_pk_bf16_f32 v78, v78, s0
	ds_write_b16 v155, v78 offset:3808
	v_mul_f32_e32 v78, v81, v80
	v_cvt_pk_bf16_f32 v78, v78, s0
	ds_write_b16 v155, v78 offset:4080
	ds_write_b16 v155, v77 offset:21216
	ds_write_b16_d16_hi v155, v77 offset:21488
	ds_write_b128 v156, v[66:69] offset:34816
	ds_write_b128 v156, v[74:77] offset:34832
	s_and_saveexec_b64 vcc, s[40:41]
	s_cbranch_execz .LBB0_1686
	v_add_f32_e32 v66, v70, v71
	v_add_f32_e32 v66, v66, v72
	v_add_f32_e32 v66, v66, v73
	v_mul_f32_e32 v66, 0x3fb8aa3b, v66
	v_exp_f32_e32 v66, v66
	ds_write_b32 v153, v66
